# input-projection epilogues (A and B): per-row-group sum of squares via v_pk_mul_f32 + 7 v_pk_fma_f32 + v_add (f32 fused, 14 fewer VALU per row group); on top of v64
# speedup vs baseline: 1.0062x; 1.0062x over previous
; __device__ __forceinline__ float sum_x16(float v) { float a, b; swap16(v, a, b); return a + b; }
; __device__ __forceinline__ float sum_x32(float v) { float a, b; swap32(v, a, b); return a + b; }
; __device__ __forceinline__ void st16_wt(void* p, u32x4 v) { if (WT_STORES) asm volatile("global_store_dwordx4 %0, %1, off sc1\n\ts_nop 1" :: "v"(p), "v"(v) : "memory"); else *(u32x4*)p = v; }
; __device__ __forceinline__ unsigned cvt_pk_bf16(float lo, float hi) { unsigned r; asm volatile("v_cvt_pk_bf16_f32 %0, %1, %2" : "=v"(r) : "v"(lo), "v"(hi)); return r; }
;     __device__ __forceinline__ void operator()(const f32x4 (&acc)[2][2][4][2], const Unit& u, int wr, int wc, int fr, int fq, const bool reuse, PG8_LAS float* rscr, PG8_LAS const float* gains) const {
;     ...
;                 if (type < 2) {
;                     float ss = 0.f;
; #pragma unroll
;                     for (int bj = 0; bj < 2; ++bj)
; #pragma unroll
;                         for (int n = 0; n < 2; ++n) { const f32x4 x = v[bj][n]; ss += (x[0] * x[0] + x[1] * x[1]) + (x[2] * x[2] + x[3] * x[3]); }
;                     ss = sum_x16(ss); ss = sum_x32(ss);
;                     const float inv = __builtin_amdgcn_rsqf(ss * (1.0f / 64.0f) + RMS_EPS);
; #pragma unroll
;                     for (int bj = 0; bj < 2; ++bj)
; #pragma unroll
;                         for (int n = 0; n < 2; ++n) v[bj][n] = v[bj][n] * gv[bj][n] * inv;
;                 }
;                 bf16_t* p = p0 + (size_t)(8 * ai + m) * step16;
; #pragma unroll
;                 for (int bj = 0; bj < 2; ++bj) { u32x4 w; w.x = cvt_pk_bf16(v[bj][0][0], v[bj][0][1]); w.y = cvt_pk_bf16(v[bj][0][2], v[bj][0][3]); w.z = cvt_pk_bf16(v[bj][1][0], v[bj][1][1]); w.w = cvt_pk_bf16(v[bj][1][2], v[bj][1][3]);
;                     st16_wt(p + 32 * bj, w); }
.LBB0_231:
	v_pk_mul_f32 v[188:189], v[128:129], v[128:129]
	v_pk_fma_f32 v[188:189], v[130:131], v[130:131], v[188:189]
	v_pk_fma_f32 v[188:189], v[132:133], v[132:133], v[188:189]
	v_pk_fma_f32 v[188:189], v[134:135], v[134:135], v[188:189]
	v_pk_fma_f32 v[188:189], v[136:137], v[136:137], v[188:189]
	v_pk_fma_f32 v[188:189], v[138:139], v[138:139], v[188:189]
	v_pk_fma_f32 v[188:189], v[140:141], v[140:141], v[188:189]
	v_pk_fma_f32 v[188:189], v[142:143], v[142:143], v[188:189]
	v_add_f32_e32 v183, v188, v189
	v_mov_b32_e32 v185, v183
	s_nop 1
	v_permlane16_swap_b32_e32 v183, v185
	v_add_f32_e32 v183, v183, v185
	v_mov_b32_e32 v185, v183
	s_nop 1
	v_permlane32_swap_b32_e32 v183, v185
	v_add_f32_e32 v183, v183, v185
	v_fmamk_f32 v183, v183, 0x3c800000, v190
	v_rsq_f32_e32 v188, v183
	s_waitcnt lgkmcnt(0)
	v_pk_mul_f32 v[134:135], v[134:135], v[158:159]
	v_pk_mul_f32 v[132:133], v[132:133], v[156:157]
	v_pk_mul_f32 v[130:131], v[130:131], v[154:155]
	v_pk_mul_f32 v[128:129], v[128:129], v[152:153]
	v_pk_mul_f32 v[142:143], v[142:143], v[150:151]
	v_pk_mul_f32 v[140:141], v[140:141], v[148:149]
	v_pk_mul_f32 v[138:139], v[138:139], v[146:147]
	v_pk_mul_f32 v[136:137], v[136:137], v[144:145]
	v_pk_mul_f32 v[134:135], v[134:135], v[188:189] op_sel_hi:[1,0]
	v_pk_mul_f32 v[132:133], v[132:133], v[188:189] op_sel_hi:[1,0]
	v_pk_mul_f32 v[130:131], v[130:131], v[188:189] op_sel_hi:[1,0]
	v_pk_mul_f32 v[128:129], v[128:129], v[188:189] op_sel_hi:[1,0]
	v_pk_mul_f32 v[142:143], v[142:143], v[188:189] op_sel_hi:[1,0]
	v_pk_mul_f32 v[140:141], v[140:141], v[188:189] op_sel_hi:[1,0]
	v_pk_mul_f32 v[138:139], v[138:139], v[188:189] op_sel_hi:[1,0]
	v_pk_mul_f32 v[136:137], v[136:137], v[188:189] op_sel_hi:[1,0]
.LBB0_232:
	v_lshl_add_u64 v[186:187], v[186:187], 0, v[160:161]
	s_and_b64 vcc, exec, s[38:39]
	v_cvt_pk_bf16_f32 v132, v132, v133
	v_cvt_pk_bf16_f32 v133, v134, v135
	v_cvt_pk_bf16_f32 v134, v128, v129
	v_cvt_pk_bf16_f32 v135, v130, v131
	global_store_dwordx4 v[186:187], v[132:135], off
	v_cvt_pk_bf16_f32 v128, v140, v141
	v_cvt_pk_bf16_f32 v129, v142, v143
	v_cvt_pk_bf16_f32 v130, v136, v137
	v_cvt_pk_bf16_f32 v131, v138, v139
	global_store_dwordx4 v[186:187], v[128:131], off offset:64
	s_cbranch_vccnz .LBB0_234
	s_nop 0
	v_pk_mul_f32 v[128:129], v[112:113], v[112:113]
	v_pk_fma_f32 v[128:129], v[114:115], v[114:115], v[128:129]
	v_pk_fma_f32 v[128:129], v[116:117], v[116:117], v[128:129]
	v_pk_fma_f32 v[128:129], v[118:119], v[118:119], v[128:129]
	v_pk_fma_f32 v[128:129], v[120:121], v[120:121], v[128:129]
	v_pk_fma_f32 v[128:129], v[122:123], v[122:123], v[128:129]
	v_pk_fma_f32 v[128:129], v[124:125], v[124:125], v[128:129]
	v_pk_fma_f32 v[128:129], v[126:127], v[126:127], v[128:129]
	v_add_f32_e32 v128, v128, v129
	v_mov_b32_e32 v129, v128
	s_nop 1
	v_permlane16_swap_b32_e32 v128, v129
	v_add_f32_e32 v128, v128, v129
	v_mov_b32_e32 v129, v128
	s_nop 1
	v_permlane32_swap_b32_e32 v128, v129
	v_add_f32_e32 v128, v128, v129
	v_fmamk_f32 v128, v128, 0x3c800000, v190
	v_rsq_f32_e32 v128, v128
	s_waitcnt lgkmcnt(0)
	v_pk_mul_f32 v[118:119], v[118:119], v[158:159]
	v_pk_mul_f32 v[116:117], v[116:117], v[156:157]
	v_pk_mul_f32 v[114:115], v[114:115], v[154:155]
	v_pk_mul_f32 v[112:113], v[112:113], v[152:153]
	v_pk_mul_f32 v[126:127], v[126:127], v[150:151]
	v_pk_mul_f32 v[124:125], v[124:125], v[148:149]
	v_pk_mul_f32 v[122:123], v[122:123], v[146:147]
	v_pk_mul_f32 v[120:121], v[120:121], v[144:145]
	v_pk_mul_f32 v[118:119], v[118:119], v[128:129] op_sel_hi:[1,0]
	v_pk_mul_f32 v[116:117], v[116:117], v[128:129] op_sel_hi:[1,0]
	v_pk_mul_f32 v[114:115], v[114:115], v[128:129] op_sel_hi:[1,0]
	v_pk_mul_f32 v[112:113], v[112:113], v[128:129] op_sel_hi:[1,0]
	v_pk_mul_f32 v[126:127], v[126:127], v[128:129] op_sel_hi:[1,0]
	v_pk_mul_f32 v[124:125], v[124:125], v[128:129] op_sel_hi:[1,0]
	v_pk_mul_f32 v[122:123], v[122:123], v[128:129] op_sel_hi:[1,0]
	v_pk_mul_f32 v[120:121], v[120:121], v[128:129] op_sel_hi:[1,0]
.LBB0_234:
	s_lshl_b32 s88, s72, 1
	v_lshl_add_u64 v[128:129], v[186:187], 0, s[88:89]
	s_and_b64 vcc, exec, s[38:39]
	v_cvt_pk_bf16_f32 v116, v116, v117
	v_cvt_pk_bf16_f32 v117, v118, v119
	v_cvt_pk_bf16_f32 v118, v112, v113
	v_cvt_pk_bf16_f32 v119, v114, v115
	global_store_dwordx4 v[128:129], v[116:119], off
	v_cvt_pk_bf16_f32 v112, v124, v125
	v_cvt_pk_bf16_f32 v113, v126, v127
	v_cvt_pk_bf16_f32 v114, v120, v121
	v_cvt_pk_bf16_f32 v115, v122, v123
	global_store_dwordx4 v[128:129], v[112:115], off offset:64
	s_cbranch_vccnz .LBB0_236
	s_nop 0
	v_pk_mul_f32 v[112:113], v[96:97], v[96:97]
	v_pk_fma_f32 v[112:113], v[98:99], v[98:99], v[112:113]
	v_pk_fma_f32 v[112:113], v[100:101], v[100:101], v[112:113]
	v_pk_fma_f32 v[112:113], v[102:103], v[102:103], v[112:113]
	v_pk_fma_f32 v[112:113], v[104:105], v[104:105], v[112:113]
	v_pk_fma_f32 v[112:113], v[106:107], v[106:107], v[112:113]
	v_pk_fma_f32 v[112:113], v[108:109], v[108:109], v[112:113]
	v_pk_fma_f32 v[112:113], v[110:111], v[110:111], v[112:113]
	v_add_f32_e32 v112, v112, v113
	v_mov_b32_e32 v113, v112
	s_nop 1
	v_permlane16_swap_b32_e32 v112, v113
	v_add_f32_e32 v112, v112, v113
	v_mov_b32_e32 v113, v112
	s_nop 1
	v_permlane32_swap_b32_e32 v112, v113
	v_add_f32_e32 v112, v112, v113
	v_fmamk_f32 v112, v112, 0x3c800000, v190
	v_rsq_f32_e32 v112, v112
	s_waitcnt lgkmcnt(0)
	v_pk_mul_f32 v[102:103], v[102:103], v[158:159]
	v_pk_mul_f32 v[100:101], v[100:101], v[156:157]
	v_pk_mul_f32 v[98:99], v[98:99], v[154:155]
	v_pk_mul_f32 v[96:97], v[96:97], v[152:153]
	v_pk_mul_f32 v[110:111], v[110:111], v[150:151]
	v_pk_mul_f32 v[108:109], v[108:109], v[148:149]
	v_pk_mul_f32 v[106:107], v[106:107], v[146:147]
	v_pk_mul_f32 v[104:105], v[104:105], v[144:145]
	v_pk_mul_f32 v[102:103], v[102:103], v[112:113] op_sel_hi:[1,0]
	v_pk_mul_f32 v[100:101], v[100:101], v[112:113] op_sel_hi:[1,0]
	v_pk_mul_f32 v[98:99], v[98:99], v[112:113] op_sel_hi:[1,0]
	v_pk_mul_f32 v[96:97], v[96:97], v[112:113] op_sel_hi:[1,0]
	v_pk_mul_f32 v[110:111], v[110:111], v[112:113] op_sel_hi:[1,0]
	v_pk_mul_f32 v[108:109], v[108:109], v[112:113] op_sel_hi:[1,0]
	v_pk_mul_f32 v[106:107], v[106:107], v[112:113] op_sel_hi:[1,0]
	v_pk_mul_f32 v[104:105], v[104:105], v[112:113] op_sel_hi:[1,0]
; __device__ __forceinline__ float sum_x16(float v) { float a, b; swap16(v, a, b); return a + b; }
; __device__ __forceinline__ float sum_x32(float v) { float a, b; swap32(v, a, b); return a + b; }
; __device__ __forceinline__ void st16_wt(void* p, u32x4 v) { if (WT_STORES) asm volatile("global_store_dwordx4 %0, %1, off sc1\n\ts_nop 1" :: "v"(p), "v"(v) : "memory"); else *(u32x4*)p = v; }
; __device__ __forceinline__ unsigned cvt_pk_bf16(float lo, float hi) { unsigned r; asm volatile("v_cvt_pk_bf16_f32 %0, %1, %2" : "=v"(r) : "v"(lo), "v"(hi)); return r; }
;     __device__ __forceinline__ void operator()(const f32x4 (&acc)[2][2][4][2], const Unit& u, int wr, int wc, int fr, int fq, const bool reuse, PG8_LAS float* rscr, PG8_LAS const float* gains) const {
;     ...
;                 if (type < 2) {
;                     float ss = 0.f;
; #pragma unroll
;                     for (int bj = 0; bj < 2; ++bj)
; #pragma unroll
;                         for (int n = 0; n < 2; ++n) { const f32x4 x = v[bj][n]; ss += (x[0] * x[0] + x[1] * x[1]) + (x[2] * x[2] + x[3] * x[3]); }
;                     ss = sum_x16(ss); ss = sum_x32(ss);
;                     const float inv = __builtin_amdgcn_rsqf(ss * (1.0f / 64.0f) + RMS_EPS);
; #pragma unroll
;                     for (int bj = 0; bj < 2; ++bj)
; #pragma unroll
;                         for (int n = 0; n < 2; ++n) v[bj][n] = v[bj][n] * gv[bj][n] * inv;
;                 }
;                 bf16_t* p = p0 + (size_t)(8 * ai + m) * step16;
; #pragma unroll
;                 for (int bj = 0; bj < 2; ++bj) { u32x4 w; w.x = cvt_pk_bf16(v[bj][0][0], v[bj][0][1]); w.y = cvt_pk_bf16(v[bj][0][2], v[bj][0][3]); w.z = cvt_pk_bf16(v[bj][1][0], v[bj][1][1]); w.w = cvt_pk_bf16(v[bj][1][2], v[bj][1][3]);
;                     st16_wt(p + 32 * bj, w); }
.LBB0_236:
	s_nop 0
	v_lshl_add_u64 v[112:113], v[128:129], 0, s[88:89]
	s_and_b64 vcc, exec, s[38:39]
	v_cvt_pk_bf16_f32 v100, v100, v101
	v_cvt_pk_bf16_f32 v101, v102, v103
	v_cvt_pk_bf16_f32 v102, v96, v97
	v_cvt_pk_bf16_f32 v103, v98, v99
	global_store_dwordx4 v[112:113], v[100:103], off
	v_cvt_pk_bf16_f32 v96, v108, v109
	v_cvt_pk_bf16_f32 v97, v110, v111
	v_cvt_pk_bf16_f32 v98, v104, v105
	v_cvt_pk_bf16_f32 v99, v106, v107
	global_store_dwordx4 v[112:113], v[96:99], off offset:64
	s_cbranch_vccnz .LBB0_238
	s_nop 0
	v_pk_mul_f32 v[96:97], v[80:81], v[80:81]
	v_pk_fma_f32 v[96:97], v[82:83], v[82:83], v[96:97]
	v_pk_fma_f32 v[96:97], v[84:85], v[84:85], v[96:97]
	v_pk_fma_f32 v[96:97], v[86:87], v[86:87], v[96:97]
	v_pk_fma_f32 v[96:97], v[88:89], v[88:89], v[96:97]
	v_pk_fma_f32 v[96:97], v[90:91], v[90:91], v[96:97]
	v_pk_fma_f32 v[96:97], v[92:93], v[92:93], v[96:97]
	v_pk_fma_f32 v[96:97], v[94:95], v[94:95], v[96:97]
	v_add_f32_e32 v96, v96, v97
	v_mov_b32_e32 v97, v96
	s_nop 1
	v_permlane16_swap_b32_e32 v96, v97
	v_add_f32_e32 v96, v96, v97
	v_mov_b32_e32 v97, v96
	s_nop 1
	v_permlane32_swap_b32_e32 v96, v97
	v_add_f32_e32 v96, v96, v97
	v_fmamk_f32 v96, v96, 0x3c800000, v190
	v_rsq_f32_e32 v96, v96
	s_waitcnt lgkmcnt(0)
	v_pk_mul_f32 v[86:87], v[86:87], v[158:159]
	v_pk_mul_f32 v[84:85], v[84:85], v[156:157]
	v_pk_mul_f32 v[82:83], v[82:83], v[154:155]
	v_pk_mul_f32 v[80:81], v[80:81], v[152:153]
	v_pk_mul_f32 v[94:95], v[94:95], v[150:151]
	v_pk_mul_f32 v[92:93], v[92:93], v[148:149]
	v_pk_mul_f32 v[90:91], v[90:91], v[146:147]
	v_pk_mul_f32 v[88:89], v[88:89], v[144:145]
	v_pk_mul_f32 v[86:87], v[86:87], v[96:97] op_sel_hi:[1,0]
	v_pk_mul_f32 v[84:85], v[84:85], v[96:97] op_sel_hi:[1,0]
	v_pk_mul_f32 v[82:83], v[82:83], v[96:97] op_sel_hi:[1,0]
	v_pk_mul_f32 v[80:81], v[80:81], v[96:97] op_sel_hi:[1,0]
	v_pk_mul_f32 v[94:95], v[94:95], v[96:97] op_sel_hi:[1,0]
	v_pk_mul_f32 v[92:93], v[92:93], v[96:97] op_sel_hi:[1,0]
	v_pk_mul_f32 v[90:91], v[90:91], v[96:97] op_sel_hi:[1,0]
	v_pk_mul_f32 v[88:89], v[88:89], v[96:97] op_sel_hi:[1,0]
.LBB0_238:
	s_nop 0
	v_lshl_add_u64 v[96:97], v[112:113], 0, s[88:89]
	s_and_b64 vcc, exec, s[38:39]
	v_cvt_pk_bf16_f32 v84, v84, v85
	v_cvt_pk_bf16_f32 v85, v86, v87
	v_cvt_pk_bf16_f32 v86, v80, v81
	v_cvt_pk_bf16_f32 v87, v82, v83
	global_store_dwordx4 v[96:97], v[84:87], off
	v_cvt_pk_bf16_f32 v80, v92, v93
	v_cvt_pk_bf16_f32 v81, v94, v95
	v_cvt_pk_bf16_f32 v82, v88, v89
	v_cvt_pk_bf16_f32 v83, v90, v91
	global_store_dwordx4 v[96:97], v[80:83], off offset:64
	s_cbranch_vccnz .LBB0_240
	s_nop 0
	v_pk_mul_f32 v[80:81], v[64:65], v[64:65]
	v_pk_fma_f32 v[80:81], v[66:67], v[66:67], v[80:81]
	v_pk_fma_f32 v[80:81], v[68:69], v[68:69], v[80:81]
	v_pk_fma_f32 v[80:81], v[70:71], v[70:71], v[80:81]
	v_pk_fma_f32 v[80:81], v[72:73], v[72:73], v[80:81]
	v_pk_fma_f32 v[80:81], v[74:75], v[74:75], v[80:81]
	v_pk_fma_f32 v[80:81], v[76:77], v[76:77], v[80:81]
	v_pk_fma_f32 v[80:81], v[78:79], v[78:79], v[80:81]
	v_add_f32_e32 v80, v80, v81
	v_mov_b32_e32 v81, v80
	s_nop 1
	v_permlane16_swap_b32_e32 v80, v81
	v_add_f32_e32 v80, v80, v81
	v_mov_b32_e32 v81, v80
	s_nop 1
	v_permlane32_swap_b32_e32 v80, v81
	v_add_f32_e32 v80, v80, v81
	v_fmamk_f32 v80, v80, 0x3c800000, v190
	v_rsq_f32_e32 v80, v80
	s_waitcnt lgkmcnt(0)
	v_pk_mul_f32 v[70:71], v[70:71], v[158:159]
	v_pk_mul_f32 v[68:69], v[68:69], v[156:157]
	v_pk_mul_f32 v[66:67], v[66:67], v[154:155]
	v_pk_mul_f32 v[64:65], v[64:65], v[152:153]
	v_pk_mul_f32 v[78:79], v[78:79], v[150:151]
	v_pk_mul_f32 v[76:77], v[76:77], v[148:149]
	v_pk_mul_f32 v[74:75], v[74:75], v[146:147]
	v_pk_mul_f32 v[72:73], v[72:73], v[144:145]
	v_pk_mul_f32 v[70:71], v[70:71], v[80:81] op_sel_hi:[1,0]
	v_pk_mul_f32 v[68:69], v[68:69], v[80:81] op_sel_hi:[1,0]
	v_pk_mul_f32 v[66:67], v[66:67], v[80:81] op_sel_hi:[1,0]
	v_pk_mul_f32 v[64:65], v[64:65], v[80:81] op_sel_hi:[1,0]
	v_pk_mul_f32 v[78:79], v[78:79], v[80:81] op_sel_hi:[1,0]
	v_pk_mul_f32 v[76:77], v[76:77], v[80:81] op_sel_hi:[1,0]
	v_pk_mul_f32 v[74:75], v[74:75], v[80:81] op_sel_hi:[1,0]
	v_pk_mul_f32 v[72:73], v[72:73], v[80:81] op_sel_hi:[1,0]
.LBB0_240:
	s_nop 0
	v_mad_u64_u32 v[80:81], s[12:13], s72, 10, v[96:97]
	v_mov_b32_e32 v254, v80
	v_mov_b32_e32 v255, v81
	s_and_b64 vcc, exec, s[38:39]
	v_cvt_pk_bf16_f32 v68, v68, v69
	v_cvt_pk_bf16_f32 v69, v70, v71
	v_cvt_pk_bf16_f32 v70, v64, v65
	v_cvt_pk_bf16_f32 v71, v66, v67
	v_mov_b32_e32 v244, v68
	v_mov_b32_e32 v245, v69
	v_mov_b32_e32 v246, v70
	v_mov_b32_e32 v247, v71
	v_cvt_pk_bf16_f32 v64, v76, v77
	v_cvt_pk_bf16_f32 v65, v78, v79
	v_cvt_pk_bf16_f32 v66, v72, v73
	v_cvt_pk_bf16_f32 v67, v74, v75
	v_mov_b32_e32 v248, v64
	v_mov_b32_e32 v249, v65
	v_mov_b32_e32 v250, v66
	v_mov_b32_e32 v251, v67
	s_cbranch_vccnz .LBB0_242
	s_nop 0
	v_pk_mul_f32 v[64:65], v[48:49], v[48:49]
	v_pk_fma_f32 v[64:65], v[50:51], v[50:51], v[64:65]
	v_pk_fma_f32 v[64:65], v[52:53], v[52:53], v[64:65]
	v_pk_fma_f32 v[64:65], v[54:55], v[54:55], v[64:65]
	v_pk_fma_f32 v[64:65], v[56:57], v[56:57], v[64:65]
	v_pk_fma_f32 v[64:65], v[58:59], v[58:59], v[64:65]
	v_pk_fma_f32 v[64:65], v[60:61], v[60:61], v[64:65]
	v_pk_fma_f32 v[64:65], v[62:63], v[62:63], v[64:65]
	v_add_f32_e32 v64, v64, v65
	v_mov_b32_e32 v65, v64
	s_nop 1
	v_permlane16_swap_b32_e32 v64, v65
	v_add_f32_e32 v64, v64, v65
	v_mov_b32_e32 v65, v64
	s_nop 1
	v_permlane32_swap_b32_e32 v64, v65
	v_add_f32_e32 v64, v64, v65
	v_fmamk_f32 v64, v64, 0x3c800000, v190
	v_rsq_f32_e32 v64, v64
	s_waitcnt lgkmcnt(0)
	v_pk_mul_f32 v[54:55], v[54:55], v[158:159]
	v_pk_mul_f32 v[52:53], v[52:53], v[156:157]
	v_pk_mul_f32 v[50:51], v[50:51], v[154:155]
	v_pk_mul_f32 v[48:49], v[48:49], v[152:153]
	v_pk_mul_f32 v[62:63], v[62:63], v[150:151]
	v_pk_mul_f32 v[60:61], v[60:61], v[148:149]
	v_pk_mul_f32 v[58:59], v[58:59], v[146:147]
	v_pk_mul_f32 v[56:57], v[56:57], v[144:145]
	v_pk_mul_f32 v[54:55], v[54:55], v[64:65] op_sel_hi:[1,0]
	v_pk_mul_f32 v[52:53], v[52:53], v[64:65] op_sel_hi:[1,0]
	v_pk_mul_f32 v[50:51], v[50:51], v[64:65] op_sel_hi:[1,0]
	v_pk_mul_f32 v[48:49], v[48:49], v[64:65] op_sel_hi:[1,0]
	v_pk_mul_f32 v[62:63], v[62:63], v[64:65] op_sel_hi:[1,0]
	v_pk_mul_f32 v[60:61], v[60:61], v[64:65] op_sel_hi:[1,0]
	v_pk_mul_f32 v[58:59], v[58:59], v[64:65] op_sel_hi:[1,0]
	v_pk_mul_f32 v[56:57], v[56:57], v[64:65] op_sel_hi:[1,0]
; __device__ __forceinline__ float sum_x16(float v) { float a, b; swap16(v, a, b); return a + b; }
; __device__ __forceinline__ float sum_x32(float v) { float a, b; swap32(v, a, b); return a + b; }
; __device__ __forceinline__ void st16_wt(void* p, u32x4 v) { if (WT_STORES) asm volatile("global_store_dwordx4 %0, %1, off sc1\n\ts_nop 1" :: "v"(p), "v"(v) : "memory"); else *(u32x4*)p = v; }
; __device__ __forceinline__ unsigned cvt_pk_bf16(float lo, float hi) { unsigned r; asm volatile("v_cvt_pk_bf16_f32 %0, %1, %2" : "=v"(r) : "v"(lo), "v"(hi)); return r; }
;     __device__ __forceinline__ void operator()(const f32x4 (&acc)[2][2][4][2], const Unit& u, int wr, int wc, int fr, int fq, const bool reuse, PG8_LAS float* rscr, PG8_LAS const float* gains) const {
;     ...
;                 if (type < 2) {
;                     float ss = 0.f;
; #pragma unroll
;                     for (int bj = 0; bj < 2; ++bj)
; #pragma unroll
;                         for (int n = 0; n < 2; ++n) { const f32x4 x = v[bj][n]; ss += (x[0] * x[0] + x[1] * x[1]) + (x[2] * x[2] + x[3] * x[3]); }
;                     ss = sum_x16(ss); ss = sum_x32(ss);
;                     const float inv = __builtin_amdgcn_rsqf(ss * (1.0f / 64.0f) + RMS_EPS);
; #pragma unroll
;                     for (int bj = 0; bj < 2; ++bj)
; #pragma unroll
;                         for (int n = 0; n < 2; ++n) v[bj][n] = v[bj][n] * gv[bj][n] * inv;
;                 }
;                 bf16_t* p = p0 + (size_t)(8 * ai + m) * step16;
; #pragma unroll
;                 for (int bj = 0; bj < 2; ++bj) { u32x4 w; w.x = cvt_pk_bf16(v[bj][0][0], v[bj][0][1]); w.y = cvt_pk_bf16(v[bj][0][2], v[bj][0][3]); w.z = cvt_pk_bf16(v[bj][1][0], v[bj][1][1]); w.w = cvt_pk_bf16(v[bj][1][2], v[bj][1][3]);
;                     st16_wt(p + 32 * bj, w); }
.LBB0_242:
	s_nop 0
	v_lshl_add_u64 v[64:65], v[80:81], 0, s[88:89]
	s_and_b64 vcc, exec, s[38:39]
	v_cvt_pk_bf16_f32 v52, v52, v53
	v_cvt_pk_bf16_f32 v53, v54, v55
	v_cvt_pk_bf16_f32 v54, v48, v49
	v_cvt_pk_bf16_f32 v55, v50, v51
	v_mov_b32_e32 v214, v52
	v_mov_b32_e32 v215, v53
	v_mov_b32_e32 v216, v54
	v_mov_b32_e32 v217, v55
	v_cvt_pk_bf16_f32 v48, v60, v61
	v_cvt_pk_bf16_f32 v49, v62, v63
	v_cvt_pk_bf16_f32 v50, v56, v57
	v_cvt_pk_bf16_f32 v51, v58, v59
	v_mov_b32_e32 v218, v48
	v_mov_b32_e32 v219, v49
	v_mov_b32_e32 v220, v50
	v_mov_b32_e32 v221, v51
	s_cbranch_vccnz .LBB0_244
	s_nop 0
	v_pk_mul_f32 v[48:49], v[32:33], v[32:33]
	v_pk_fma_f32 v[48:49], v[34:35], v[34:35], v[48:49]
	v_pk_fma_f32 v[48:49], v[36:37], v[36:37], v[48:49]
	v_pk_fma_f32 v[48:49], v[38:39], v[38:39], v[48:49]
	v_pk_fma_f32 v[48:49], v[40:41], v[40:41], v[48:49]
	v_pk_fma_f32 v[48:49], v[42:43], v[42:43], v[48:49]
	v_pk_fma_f32 v[48:49], v[44:45], v[44:45], v[48:49]
	v_pk_fma_f32 v[48:49], v[46:47], v[46:47], v[48:49]
	v_add_f32_e32 v48, v48, v49
	v_mov_b32_e32 v49, v48
	s_nop 1
	v_permlane16_swap_b32_e32 v48, v49
	v_add_f32_e32 v48, v48, v49
	v_mov_b32_e32 v49, v48
	s_nop 1
	v_permlane32_swap_b32_e32 v48, v49
	v_add_f32_e32 v48, v48, v49
	v_fmamk_f32 v48, v48, 0x3c800000, v190
	v_rsq_f32_e32 v48, v48
	s_waitcnt lgkmcnt(0)
	v_pk_mul_f32 v[38:39], v[38:39], v[158:159]
	v_pk_mul_f32 v[36:37], v[36:37], v[156:157]
	v_pk_mul_f32 v[34:35], v[34:35], v[154:155]
	v_pk_mul_f32 v[32:33], v[32:33], v[152:153]
	v_pk_mul_f32 v[46:47], v[46:47], v[150:151]
	v_pk_mul_f32 v[44:45], v[44:45], v[148:149]
	v_pk_mul_f32 v[42:43], v[42:43], v[146:147]
	v_pk_mul_f32 v[40:41], v[40:41], v[144:145]
	v_pk_mul_f32 v[38:39], v[38:39], v[48:49] op_sel_hi:[1,0]
	v_pk_mul_f32 v[36:37], v[36:37], v[48:49] op_sel_hi:[1,0]
	v_pk_mul_f32 v[34:35], v[34:35], v[48:49] op_sel_hi:[1,0]
	v_pk_mul_f32 v[32:33], v[32:33], v[48:49] op_sel_hi:[1,0]
	v_pk_mul_f32 v[46:47], v[46:47], v[48:49] op_sel_hi:[1,0]
	v_pk_mul_f32 v[44:45], v[44:45], v[48:49] op_sel_hi:[1,0]
	v_pk_mul_f32 v[42:43], v[42:43], v[48:49] op_sel_hi:[1,0]
	v_pk_mul_f32 v[40:41], v[40:41], v[48:49] op_sel_hi:[1,0]
.LBB0_244:
	s_nop 0
	v_lshl_add_u64 v[48:49], v[64:65], 0, s[88:89]
	s_and_b64 vcc, exec, s[38:39]
	v_cvt_pk_bf16_f32 v36, v36, v37
	v_cvt_pk_bf16_f32 v37, v38, v39
	v_cvt_pk_bf16_f32 v38, v32, v33
	v_cvt_pk_bf16_f32 v39, v34, v35
	v_mov_b32_e32 v0, v36
	v_mov_b32_e32 v1, v37
	v_mov_b32_e32 v2, v38
	v_mov_b32_e32 v3, v39
	v_cvt_pk_bf16_f32 v32, v44, v45
	v_cvt_pk_bf16_f32 v33, v46, v47
	v_cvt_pk_bf16_f32 v34, v40, v41
	v_cvt_pk_bf16_f32 v35, v42, v43
	v_mov_b32_e32 v4, v32
	v_mov_b32_e32 v5, v33
	v_mov_b32_e32 v6, v34
	v_mov_b32_e32 v7, v35
	s_cbranch_vccnz .LBB0_246
	s_nop 0
	v_pk_mul_f32 v[32:33], v[16:17], v[16:17]
	v_pk_fma_f32 v[32:33], v[18:19], v[18:19], v[32:33]
	v_pk_fma_f32 v[32:33], v[20:21], v[20:21], v[32:33]
	v_pk_fma_f32 v[32:33], v[22:23], v[22:23], v[32:33]
	v_pk_fma_f32 v[32:33], v[24:25], v[24:25], v[32:33]
	v_pk_fma_f32 v[32:33], v[26:27], v[26:27], v[32:33]
	v_pk_fma_f32 v[32:33], v[28:29], v[28:29], v[32:33]
	v_pk_fma_f32 v[32:33], v[30:31], v[30:31], v[32:33]
	v_add_f32_e32 v32, v32, v33
	v_mov_b32_e32 v33, v32
	s_nop 1
	v_permlane16_swap_b32_e32 v32, v33
	v_add_f32_e32 v32, v32, v33
	v_mov_b32_e32 v33, v32
	s_nop 1
	v_permlane32_swap_b32_e32 v32, v33
	v_add_f32_e32 v32, v32, v33
	v_fmamk_f32 v32, v32, 0x3c800000, v190
	v_rsq_f32_e32 v32, v32
	s_waitcnt lgkmcnt(0)
	v_pk_mul_f32 v[22:23], v[22:23], v[158:159]
	v_pk_mul_f32 v[20:21], v[20:21], v[156:157]
	v_pk_mul_f32 v[18:19], v[18:19], v[154:155]
	v_pk_mul_f32 v[16:17], v[16:17], v[152:153]
	v_pk_mul_f32 v[26:27], v[26:27], v[150:151]
	v_pk_mul_f32 v[24:25], v[24:25], v[148:149]
	v_pk_mul_f32 v[30:31], v[30:31], v[146:147]
	v_pk_mul_f32 v[28:29], v[28:29], v[144:145]
	v_pk_mul_f32 v[22:23], v[22:23], v[32:33] op_sel_hi:[1,0]
	v_pk_mul_f32 v[20:21], v[20:21], v[32:33] op_sel_hi:[1,0]
	v_pk_mul_f32 v[18:19], v[18:19], v[32:33] op_sel_hi:[1,0]
	v_pk_mul_f32 v[16:17], v[16:17], v[32:33] op_sel_hi:[1,0]
	v_pk_mul_f32 v[26:27], v[26:27], v[32:33] op_sel_hi:[1,0]
	v_pk_mul_f32 v[24:25], v[24:25], v[32:33] op_sel_hi:[1,0]
	v_pk_mul_f32 v[30:31], v[30:31], v[32:33] op_sel_hi:[1,0]
	v_pk_mul_f32 v[28:29], v[28:29], v[32:33] op_sel_hi:[1,0]

; __device__ __forceinline__ float sum_x16(float v) { float a, b; swap16(v, a, b); return a + b; }
; __device__ __forceinline__ float sum_x32(float v) { float a, b; swap32(v, a, b); return a + b; }
; __device__ __forceinline__ void st16_wt(void* p, u32x4 v) { if (WT_STORES) asm volatile("global_store_dwordx4 %0, %1, off sc1\n\ts_nop 1" :: "v"(p), "v"(v) : "memory"); else *(u32x4*)p = v; }
; __device__ __forceinline__ unsigned cvt_pk_bf16(float lo, float hi) { unsigned r; asm volatile("v_cvt_pk_bf16_f32 %0, %1, %2" : "=v"(r) : "v"(lo), "v"(hi)); return r; }
;     __device__ __forceinline__ void operator()(const f32x4 (&acc)[2][2][4][2], const Unit& u, int wr, int wc, int fr, int fq, const bool reuse, PG8_LAS float* rscr, PG8_LAS const float* gains) const {
;     ...
; #pragma unroll
;         for (int ai = 0; ai < 2; ++ai)
; #pragma unroll
;             for (int m = 0; m < 4; ++m) {
;                 const int r = u.pm * BM + ai * HALF + wr * 64 + m * 16 + fr;
;                 const float rsv = (MODE == 0) ? 1.0f : rsvv[ai][m];
;                 f32x4 v[2][2];
; #pragma unroll
;                 for (int bj = 0; bj < 2; ++bj)
; #pragma unroll
;                     for (int n = 0; n < 2; ++n) v[bj][n] = acc[ai][bj][m][n] * rsv;
;                 if (type < 2) {
;                     float ss = 0.f;
; #pragma unroll
;                     for (int bj = 0; bj < 2; ++bj)
; #pragma unroll
;                         for (int n = 0; n < 2; ++n) { const f32x4 x = v[bj][n]; ss += (x[0] * x[0] + x[1] * x[1]) + (x[2] * x[2] + x[3] * x[3]); }
;                     ss = sum_x16(ss); ss = sum_x32(ss);
;                     const float inv = __builtin_amdgcn_rsqf(ss * (1.0f / 64.0f) + RMS_EPS);
; #pragma unroll
;                     for (int bj = 0; bj < 2; ++bj)
; #pragma unroll
;                         for (int n = 0; n < 2; ++n) v[bj][n] = v[bj][n] * gv[bj][n] * inv;
;                 }
;                 bf16_t* p = p0 + (size_t)(8 * ai + m) * step16;
; #pragma unroll
;                 for (int bj = 0; bj < 2; ++bj) { u32x4 w; w.x = cvt_pk_bf16(v[bj][0][0], v[bj][0][1]); w.y = cvt_pk_bf16(v[bj][0][2], v[bj][0][3]); w.z = cvt_pk_bf16(v[bj][1][0], v[bj][1][1]); w.w = cvt_pk_bf16(v[bj][1][2], v[bj][1][3]);
;                     st16_wt(p + 32 * bj, w); }
.LBB0_561:
	v_pk_mul_f32 v[154:155], v[128:129], v[194:195] op_sel_hi:[1,0]
	v_cndmask_b32_e64 v128, 0, 1, s[24:25]
	v_pk_mul_f32 v[134:135], v[134:135], v[194:195] op_sel_hi:[1,0]
	v_pk_mul_f32 v[150:151], v[132:133], v[194:195] op_sel_hi:[1,0]
	v_pk_mul_f32 v[146:147], v[130:131], v[194:195] op_sel_hi:[1,0]
	v_pk_mul_f32 v[130:131], v[142:143], v[194:195] op_sel_hi:[1,0]
	v_pk_mul_f32 v[140:141], v[140:141], v[194:195] op_sel_hi:[1,0]
	v_pk_mul_f32 v[132:133], v[138:139], v[194:195] op_sel_hi:[1,0]
	v_cmp_ne_u32_e64 s[38:39], 1, v128
	s_andn2_b64 vcc, exec, s[24:25]
	v_pk_mul_f32 v[136:137], v[136:137], v[194:195] op_sel_hi:[1,0]
	s_cbranch_vccnz .LBB0_563
	v_pk_mul_f32 v[128:129], v[130:131], v[130:131]
	v_pk_fma_f32 v[128:129], v[132:133], v[132:133], v[128:129]
	v_pk_fma_f32 v[128:129], v[134:135], v[134:135], v[128:129]
	v_pk_fma_f32 v[128:129], v[136:137], v[136:137], v[128:129]
	v_pk_fma_f32 v[128:129], v[140:141], v[140:141], v[128:129]
	v_pk_fma_f32 v[128:129], v[146:147], v[146:147], v[128:129]
	v_pk_fma_f32 v[128:129], v[150:151], v[150:151], v[128:129]
	v_pk_fma_f32 v[128:129], v[154:155], v[154:155], v[128:129]
	v_add_f32_e32 v128, v128, v129
	v_mov_b32_e32 v129, v128
	s_nop 1
	v_permlane16_swap_b32_e32 v128, v129
	v_add_f32_e32 v128, v128, v129
	v_mov_b32_e32 v129, v128
	s_nop 1
	v_permlane32_swap_b32_e32 v128, v129
	v_add_f32_e32 v128, v128, v129
	v_fmamk_f32 v128, v128, 0x3c800000, v201
	v_rsq_f32_e32 v128, v128
	s_waitcnt lgkmcnt(0)
	v_pk_mul_f32 v[138:139], v[124:125], v[150:151]
	v_pk_mul_f32 v[134:135], v[126:127], v[134:135]
	v_pk_mul_f32 v[142:143], v[120:121], v[154:155]
	v_pk_mul_f32 v[150:151], v[138:139], v[128:129] op_sel_hi:[1,0]
	v_pk_mul_f32 v[138:139], v[122:123], v[146:147]
	v_pk_mul_f32 v[130:131], v[118:119], v[130:131]
	v_pk_mul_f32 v[146:147], v[138:139], v[128:129] op_sel_hi:[1,0]
	v_pk_mul_f32 v[138:139], v[116:117], v[140:141]
	v_pk_mul_f32 v[132:133], v[114:115], v[132:133]
	v_pk_mul_f32 v[136:137], v[112:113], v[136:137]
	v_pk_mul_f32 v[134:135], v[134:135], v[128:129] op_sel_hi:[1,0]
	v_pk_mul_f32 v[154:155], v[142:143], v[128:129] op_sel_hi:[1,0]
	v_pk_mul_f32 v[130:131], v[130:131], v[128:129] op_sel_hi:[1,0]
	v_pk_mul_f32 v[140:141], v[138:139], v[128:129] op_sel_hi:[1,0]
	v_pk_mul_f32 v[132:133], v[132:133], v[128:129] op_sel_hi:[1,0]
	v_pk_mul_f32 v[136:137], v[136:137], v[128:129] op_sel_hi:[1,0]
.LBB0_563:
	v_lshl_add_u64 v[128:129], v[192:193], 0, v[180:181]
	v_cvt_pk_bf16_f32 v192, v150, v151
	v_cvt_pk_bf16_f32 v193, v134, v135
	v_cvt_pk_bf16_f32 v194, v154, v155
	v_cvt_pk_bf16_f32 v195, v146, v147
	global_store_dwordx4 v[128:129], v[192:195], off
	v_cvt_pk_bf16_f32 v134, v140, v141
	v_cvt_pk_bf16_f32 v135, v130, v131
	v_cvt_pk_bf16_f32 v136, v136, v137
	v_cvt_pk_bf16_f32 v137, v132, v133
	global_store_dwordx4 v[128:129], v[134:137], off offset:64
	v_pk_mul_f32 v[102:103], v[102:103], v[168:169] op_sel_hi:[1,0]
	v_pk_mul_f32 v[132:133], v[100:101], v[168:169] op_sel_hi:[1,0]
	v_pk_mul_f32 v[130:131], v[98:99], v[168:169] op_sel_hi:[1,0]
	v_pk_mul_f32 v[134:135], v[96:97], v[168:169] op_sel_hi:[1,0]
	v_pk_mul_f32 v[98:99], v[110:111], v[168:169] op_sel_hi:[1,0]
	v_pk_mul_f32 v[108:109], v[108:109], v[168:169] op_sel_hi:[1,0]
	v_pk_mul_f32 v[100:101], v[106:107], v[168:169] op_sel_hi:[1,0]
	s_and_b64 vcc, exec, s[38:39]
	v_pk_mul_f32 v[104:105], v[104:105], v[168:169] op_sel_hi:[1,0]
	s_cbranch_vccnz .LBB0_565
	v_pk_mul_f32 v[96:97], v[98:99], v[98:99]
	v_pk_fma_f32 v[96:97], v[100:101], v[100:101], v[96:97]
	v_pk_fma_f32 v[96:97], v[102:103], v[102:103], v[96:97]
	v_pk_fma_f32 v[96:97], v[104:105], v[104:105], v[96:97]
	v_pk_fma_f32 v[96:97], v[108:109], v[108:109], v[96:97]
	v_pk_fma_f32 v[96:97], v[130:131], v[130:131], v[96:97]
	v_pk_fma_f32 v[96:97], v[132:133], v[132:133], v[96:97]
	v_pk_fma_f32 v[96:97], v[134:135], v[134:135], v[96:97]
	v_add_f32_e32 v96, v96, v97
	v_mov_b32_e32 v97, v96
	s_nop 1
	v_permlane16_swap_b32_e32 v96, v97
	v_add_f32_e32 v96, v96, v97
	v_mov_b32_e32 v97, v96
	s_nop 1
	v_permlane32_swap_b32_e32 v96, v97
	v_add_f32_e32 v96, v96, v97
	v_fmamk_f32 v96, v96, 0x3c800000, v201
	v_rsq_f32_e32 v96, v96
	s_waitcnt lgkmcnt(0)
	v_pk_mul_f32 v[106:107], v[124:125], v[132:133]
	v_pk_mul_f32 v[102:103], v[126:127], v[102:103]
	v_pk_mul_f32 v[110:111], v[120:121], v[134:135]
	v_pk_mul_f32 v[132:133], v[106:107], v[96:97] op_sel_hi:[1,0]
	v_pk_mul_f32 v[106:107], v[122:123], v[130:131]
	v_pk_mul_f32 v[98:99], v[118:119], v[98:99]
	v_pk_mul_f32 v[130:131], v[106:107], v[96:97] op_sel_hi:[1,0]
	v_pk_mul_f32 v[106:107], v[116:117], v[108:109]
	v_pk_mul_f32 v[100:101], v[114:115], v[100:101]
	v_pk_mul_f32 v[104:105], v[112:113], v[104:105]
	v_pk_mul_f32 v[102:103], v[102:103], v[96:97] op_sel_hi:[1,0]
	v_pk_mul_f32 v[134:135], v[110:111], v[96:97] op_sel_hi:[1,0]
	v_pk_mul_f32 v[98:99], v[98:99], v[96:97] op_sel_hi:[1,0]
	v_pk_mul_f32 v[108:109], v[106:107], v[96:97] op_sel_hi:[1,0]
	v_pk_mul_f32 v[100:101], v[100:101], v[96:97] op_sel_hi:[1,0]
	v_pk_mul_f32 v[104:105], v[104:105], v[96:97] op_sel_hi:[1,0]
; __device__ __forceinline__ float sum_x16(float v) { float a, b; swap16(v, a, b); return a + b; }
; __device__ __forceinline__ float sum_x32(float v) { float a, b; swap32(v, a, b); return a + b; }
; __device__ __forceinline__ void st16_wt(void* p, u32x4 v) { if (WT_STORES) asm volatile("global_store_dwordx4 %0, %1, off sc1\n\ts_nop 1" :: "v"(p), "v"(v) : "memory"); else *(u32x4*)p = v; }
; __device__ __forceinline__ unsigned cvt_pk_bf16(float lo, float hi) { unsigned r; asm volatile("v_cvt_pk_bf16_f32 %0, %1, %2" : "=v"(r) : "v"(lo), "v"(hi)); return r; }
;     __device__ __forceinline__ void operator()(const f32x4 (&acc)[2][2][4][2], const Unit& u, int wr, int wc, int fr, int fq, const bool reuse, PG8_LAS float* rscr, PG8_LAS const float* gains) const {
;     ...
;                 if (type < 2) {
;                     float ss = 0.f;
; #pragma unroll
;                     for (int bj = 0; bj < 2; ++bj)
; #pragma unroll
;                         for (int n = 0; n < 2; ++n) { const f32x4 x = v[bj][n]; ss += (x[0] * x[0] + x[1] * x[1]) + (x[2] * x[2] + x[3] * x[3]); }
;                     ss = sum_x16(ss); ss = sum_x32(ss);
;                     const float inv = __builtin_amdgcn_rsqf(ss * (1.0f / 64.0f) + RMS_EPS);
; #pragma unroll
;                     for (int bj = 0; bj < 2; ++bj)
; #pragma unroll
;                         for (int n = 0; n < 2; ++n) v[bj][n] = v[bj][n] * gv[bj][n] * inv;
;                 }
;                 bf16_t* p = p0 + (size_t)(8 * ai + m) * step16;
; #pragma unroll
;                 for (int bj = 0; bj < 2; ++bj) { u32x4 w; w.x = cvt_pk_bf16(v[bj][0][0], v[bj][0][1]); w.y = cvt_pk_bf16(v[bj][0][2], v[bj][0][3]); w.z = cvt_pk_bf16(v[bj][1][0], v[bj][1][1]); w.w = cvt_pk_bf16(v[bj][1][2], v[bj][1][3]);
;                     st16_wt(p + 32 * bj, w); }
.LBB0_565:
	s_lshl_b32 s12, s22, 1
	v_lshl_add_u64 v[96:97], v[128:129], 0, s[12:13]
	v_cvt_pk_bf16_f32 v132, v132, v133
	v_cvt_pk_bf16_f32 v133, v102, v103
	v_cvt_pk_bf16_f32 v134, v134, v135
	v_cvt_pk_bf16_f32 v135, v130, v131
	global_store_dwordx4 v[96:97], v[132:135], off
	v_cvt_pk_bf16_f32 v102, v108, v109
	v_cvt_pk_bf16_f32 v103, v98, v99
	v_cvt_pk_bf16_f32 v104, v104, v105
	v_cvt_pk_bf16_f32 v105, v100, v101
	global_store_dwordx4 v[96:97], v[102:105], off offset:64
	v_pk_mul_f32 v[86:87], v[86:87], v[164:165] op_sel_hi:[1,0]
	v_pk_mul_f32 v[100:101], v[84:85], v[164:165] op_sel_hi:[1,0]
	v_pk_mul_f32 v[98:99], v[82:83], v[164:165] op_sel_hi:[1,0]
	v_pk_mul_f32 v[102:103], v[80:81], v[164:165] op_sel_hi:[1,0]
	v_pk_mul_f32 v[82:83], v[94:95], v[164:165] op_sel_hi:[1,0]
	v_pk_mul_f32 v[92:93], v[92:93], v[164:165] op_sel_hi:[1,0]
	v_pk_mul_f32 v[84:85], v[90:91], v[164:165] op_sel_hi:[1,0]
	s_and_b64 vcc, exec, s[38:39]
	v_pk_mul_f32 v[88:89], v[88:89], v[164:165] op_sel_hi:[1,0]
	s_cbranch_vccnz .LBB0_567
	v_pk_mul_f32 v[80:81], v[82:83], v[82:83]
	v_pk_fma_f32 v[80:81], v[84:85], v[84:85], v[80:81]
	v_pk_fma_f32 v[80:81], v[86:87], v[86:87], v[80:81]
	v_pk_fma_f32 v[80:81], v[88:89], v[88:89], v[80:81]
	v_pk_fma_f32 v[80:81], v[92:93], v[92:93], v[80:81]
	v_pk_fma_f32 v[80:81], v[98:99], v[98:99], v[80:81]
	v_pk_fma_f32 v[80:81], v[100:101], v[100:101], v[80:81]
	v_pk_fma_f32 v[80:81], v[102:103], v[102:103], v[80:81]
	v_add_f32_e32 v80, v80, v81
	v_mov_b32_e32 v81, v80
	s_nop 1
	v_permlane16_swap_b32_e32 v80, v81
	v_add_f32_e32 v80, v80, v81
	v_mov_b32_e32 v81, v80
	s_nop 1
	v_permlane32_swap_b32_e32 v80, v81
	v_add_f32_e32 v80, v80, v81
	v_fmamk_f32 v80, v80, 0x3c800000, v201
	v_rsq_f32_e32 v80, v80
	s_waitcnt lgkmcnt(0)
	v_pk_mul_f32 v[90:91], v[124:125], v[100:101]
	v_pk_mul_f32 v[86:87], v[126:127], v[86:87]
	v_pk_mul_f32 v[94:95], v[120:121], v[102:103]
	v_pk_mul_f32 v[100:101], v[90:91], v[80:81] op_sel_hi:[1,0]
	v_pk_mul_f32 v[90:91], v[122:123], v[98:99]
	v_pk_mul_f32 v[82:83], v[118:119], v[82:83]
	v_pk_mul_f32 v[98:99], v[90:91], v[80:81] op_sel_hi:[1,0]
	v_pk_mul_f32 v[90:91], v[116:117], v[92:93]
	v_pk_mul_f32 v[84:85], v[114:115], v[84:85]
	v_pk_mul_f32 v[88:89], v[112:113], v[88:89]
	v_pk_mul_f32 v[86:87], v[86:87], v[80:81] op_sel_hi:[1,0]
	v_pk_mul_f32 v[102:103], v[94:95], v[80:81] op_sel_hi:[1,0]
	v_pk_mul_f32 v[82:83], v[82:83], v[80:81] op_sel_hi:[1,0]
	v_pk_mul_f32 v[92:93], v[90:91], v[80:81] op_sel_hi:[1,0]
	v_pk_mul_f32 v[84:85], v[84:85], v[80:81] op_sel_hi:[1,0]
	v_pk_mul_f32 v[88:89], v[88:89], v[80:81] op_sel_hi:[1,0]
.LBB0_567:
	v_lshl_add_u64 v[80:81], v[96:97], 0, s[12:13]
	v_cvt_pk_bf16_f32 v94, v100, v101
	v_cvt_pk_bf16_f32 v95, v86, v87
	v_cvt_pk_bf16_f32 v96, v102, v103
	v_cvt_pk_bf16_f32 v97, v98, v99
	global_store_dwordx4 v[80:81], v[94:97], off
	v_cvt_pk_bf16_f32 v86, v92, v93
	v_cvt_pk_bf16_f32 v87, v82, v83
	v_cvt_pk_bf16_f32 v88, v88, v89
	v_cvt_pk_bf16_f32 v89, v84, v85
	global_store_dwordx4 v[80:81], v[86:89], off offset:64
	v_pk_mul_f32 v[70:71], v[70:71], v[160:161] op_sel_hi:[1,0]
	v_pk_mul_f32 v[84:85], v[68:69], v[160:161] op_sel_hi:[1,0]
	v_pk_mul_f32 v[82:83], v[66:67], v[160:161] op_sel_hi:[1,0]
	v_pk_mul_f32 v[86:87], v[64:65], v[160:161] op_sel_hi:[1,0]
	v_pk_mul_f32 v[66:67], v[78:79], v[160:161] op_sel_hi:[1,0]
	v_pk_mul_f32 v[76:77], v[76:77], v[160:161] op_sel_hi:[1,0]
	v_pk_mul_f32 v[68:69], v[74:75], v[160:161] op_sel_hi:[1,0]
	s_and_b64 vcc, exec, s[38:39]
	v_pk_mul_f32 v[72:73], v[72:73], v[160:161] op_sel_hi:[1,0]
	s_cbranch_vccnz .LBB0_569
	v_pk_mul_f32 v[64:65], v[66:67], v[66:67]
	v_pk_fma_f32 v[64:65], v[68:69], v[68:69], v[64:65]
	v_pk_fma_f32 v[64:65], v[70:71], v[70:71], v[64:65]
	v_pk_fma_f32 v[64:65], v[72:73], v[72:73], v[64:65]
	v_pk_fma_f32 v[64:65], v[76:77], v[76:77], v[64:65]
	v_pk_fma_f32 v[64:65], v[82:83], v[82:83], v[64:65]
	v_pk_fma_f32 v[64:65], v[84:85], v[84:85], v[64:65]
	v_pk_fma_f32 v[64:65], v[86:87], v[86:87], v[64:65]
	v_add_f32_e32 v64, v64, v65
	v_mov_b32_e32 v65, v64
	s_nop 1
	v_permlane16_swap_b32_e32 v64, v65
	v_add_f32_e32 v64, v64, v65
	v_mov_b32_e32 v65, v64
	s_nop 1
	v_permlane32_swap_b32_e32 v64, v65
	v_add_f32_e32 v64, v64, v65
	v_fmamk_f32 v64, v64, 0x3c800000, v201
	v_rsq_f32_e32 v64, v64
	s_waitcnt lgkmcnt(0)
	v_pk_mul_f32 v[74:75], v[124:125], v[84:85]
	v_pk_mul_f32 v[70:71], v[126:127], v[70:71]
	v_pk_mul_f32 v[78:79], v[120:121], v[86:87]
	v_pk_mul_f32 v[84:85], v[74:75], v[64:65] op_sel_hi:[1,0]
	v_pk_mul_f32 v[74:75], v[122:123], v[82:83]
	v_pk_mul_f32 v[66:67], v[118:119], v[66:67]
	v_pk_mul_f32 v[82:83], v[74:75], v[64:65] op_sel_hi:[1,0]
	v_pk_mul_f32 v[74:75], v[116:117], v[76:77]
	v_pk_mul_f32 v[68:69], v[114:115], v[68:69]
	v_pk_mul_f32 v[72:73], v[112:113], v[72:73]
	v_pk_mul_f32 v[70:71], v[70:71], v[64:65] op_sel_hi:[1,0]
	v_pk_mul_f32 v[86:87], v[78:79], v[64:65] op_sel_hi:[1,0]
	v_pk_mul_f32 v[66:67], v[66:67], v[64:65] op_sel_hi:[1,0]
	v_pk_mul_f32 v[76:77], v[74:75], v[64:65] op_sel_hi:[1,0]
	v_pk_mul_f32 v[68:69], v[68:69], v[64:65] op_sel_hi:[1,0]
	v_pk_mul_f32 v[72:73], v[72:73], v[64:65] op_sel_hi:[1,0]
; __device__ __forceinline__ float sum_x16(float v) { float a, b; swap16(v, a, b); return a + b; }
; __device__ __forceinline__ float sum_x32(float v) { float a, b; swap32(v, a, b); return a + b; }
; __device__ __forceinline__ void st16_wt(void* p, u32x4 v) { if (WT_STORES) asm volatile("global_store_dwordx4 %0, %1, off sc1\n\ts_nop 1" :: "v"(p), "v"(v) : "memory"); else *(u32x4*)p = v; }
; __device__ __forceinline__ unsigned cvt_pk_bf16(float lo, float hi) { unsigned r; asm volatile("v_cvt_pk_bf16_f32 %0, %1, %2" : "=v"(r) : "v"(lo), "v"(hi)); return r; }
;     __device__ __forceinline__ void operator()(const f32x4 (&acc)[2][2][4][2], const Unit& u, int wr, int wc, int fr, int fq, const bool reuse, PG8_LAS float* rscr, PG8_LAS const float* gains) const {
;     ...
;                 if (type < 2) {
;                     float ss = 0.f;
; #pragma unroll
;                     for (int bj = 0; bj < 2; ++bj)
; #pragma unroll
;                         for (int n = 0; n < 2; ++n) { const f32x4 x = v[bj][n]; ss += (x[0] * x[0] + x[1] * x[1]) + (x[2] * x[2] + x[3] * x[3]); }
;                     ss = sum_x16(ss); ss = sum_x32(ss);
;                     const float inv = __builtin_amdgcn_rsqf(ss * (1.0f / 64.0f) + RMS_EPS);
; #pragma unroll
;                     for (int bj = 0; bj < 2; ++bj)
; #pragma unroll
;                         for (int n = 0; n < 2; ++n) v[bj][n] = v[bj][n] * gv[bj][n] * inv;
;                 }
;                 bf16_t* p = p0 + (size_t)(8 * ai + m) * step16;
; #pragma unroll
;                 for (int bj = 0; bj < 2; ++bj) { u32x4 w; w.x = cvt_pk_bf16(v[bj][0][0], v[bj][0][1]); w.y = cvt_pk_bf16(v[bj][0][2], v[bj][0][3]); w.z = cvt_pk_bf16(v[bj][1][0], v[bj][1][1]); w.w = cvt_pk_bf16(v[bj][1][2], v[bj][1][3]);
;                     st16_wt(p + 32 * bj, w); }
.LBB0_569:
	v_lshl_add_u64 v[64:65], v[80:81], 0, s[12:13]
	v_cvt_pk_bf16_f32 v78, v84, v85
	v_cvt_pk_bf16_f32 v79, v70, v71
	v_cvt_pk_bf16_f32 v80, v86, v87
	v_cvt_pk_bf16_f32 v81, v82, v83
	global_store_dwordx4 v[64:65], v[78:81], off
	v_cvt_pk_bf16_f32 v70, v76, v77
	v_cvt_pk_bf16_f32 v71, v66, v67
	v_cvt_pk_bf16_f32 v72, v72, v73
	v_cvt_pk_bf16_f32 v73, v68, v69
	global_store_dwordx4 v[64:65], v[70:73], off offset:64
	v_pk_mul_f32 v[54:55], v[54:55], v[156:157] op_sel_hi:[1,0]
	v_pk_mul_f32 v[68:69], v[52:53], v[156:157] op_sel_hi:[1,0]
	v_pk_mul_f32 v[66:67], v[50:51], v[156:157] op_sel_hi:[1,0]
	v_pk_mul_f32 v[70:71], v[48:49], v[156:157] op_sel_hi:[1,0]
	v_pk_mul_f32 v[50:51], v[62:63], v[156:157] op_sel_hi:[1,0]
	v_pk_mul_f32 v[60:61], v[60:61], v[156:157] op_sel_hi:[1,0]
	v_pk_mul_f32 v[52:53], v[58:59], v[156:157] op_sel_hi:[1,0]
	s_and_b64 vcc, exec, s[38:39]
	v_pk_mul_f32 v[56:57], v[56:57], v[156:157] op_sel_hi:[1,0]
	s_cbranch_vccnz .LBB0_571
	v_pk_mul_f32 v[48:49], v[50:51], v[50:51]
	v_pk_fma_f32 v[48:49], v[52:53], v[52:53], v[48:49]
	v_pk_fma_f32 v[48:49], v[54:55], v[54:55], v[48:49]
	v_pk_fma_f32 v[48:49], v[56:57], v[56:57], v[48:49]
	v_pk_fma_f32 v[48:49], v[60:61], v[60:61], v[48:49]
	v_pk_fma_f32 v[48:49], v[66:67], v[66:67], v[48:49]
	v_pk_fma_f32 v[48:49], v[68:69], v[68:69], v[48:49]
	v_pk_fma_f32 v[48:49], v[70:71], v[70:71], v[48:49]
	v_add_f32_e32 v48, v48, v49
	v_mov_b32_e32 v49, v48
	s_nop 1
	v_permlane16_swap_b32_e32 v48, v49
	v_add_f32_e32 v48, v48, v49
	v_mov_b32_e32 v49, v48
	s_nop 1
	v_permlane32_swap_b32_e32 v48, v49
	v_add_f32_e32 v48, v48, v49
	v_fmamk_f32 v48, v48, 0x3c800000, v201
	v_rsq_f32_e32 v48, v48
	s_waitcnt lgkmcnt(0)
	v_pk_mul_f32 v[58:59], v[124:125], v[68:69]
	v_pk_mul_f32 v[54:55], v[126:127], v[54:55]
	v_pk_mul_f32 v[62:63], v[120:121], v[70:71]
	v_pk_mul_f32 v[68:69], v[58:59], v[48:49] op_sel_hi:[1,0]
	v_pk_mul_f32 v[58:59], v[122:123], v[66:67]
	v_pk_mul_f32 v[50:51], v[118:119], v[50:51]
	v_pk_mul_f32 v[66:67], v[58:59], v[48:49] op_sel_hi:[1,0]
	v_pk_mul_f32 v[58:59], v[116:117], v[60:61]
	v_pk_mul_f32 v[52:53], v[114:115], v[52:53]
	v_pk_mul_f32 v[56:57], v[112:113], v[56:57]
	v_pk_mul_f32 v[54:55], v[54:55], v[48:49] op_sel_hi:[1,0]
	v_pk_mul_f32 v[70:71], v[62:63], v[48:49] op_sel_hi:[1,0]
	v_pk_mul_f32 v[50:51], v[50:51], v[48:49] op_sel_hi:[1,0]
	v_pk_mul_f32 v[60:61], v[58:59], v[48:49] op_sel_hi:[1,0]
	v_pk_mul_f32 v[52:53], v[52:53], v[48:49] op_sel_hi:[1,0]
	v_pk_mul_f32 v[56:57], v[56:57], v[48:49] op_sel_hi:[1,0]
.LBB0_571:
	s_mul_i32 s22, s22, 10
	s_mov_b32 s23, s13
	v_lshl_add_u64 v[48:49], v[64:65], 0, s[22:23]
	v_cvt_pk_bf16_f32 v62, v68, v69
	v_cvt_pk_bf16_f32 v63, v54, v55
	v_cvt_pk_bf16_f32 v64, v70, v71
	v_cvt_pk_bf16_f32 v65, v66, v67
	global_store_dwordx4 v[48:49], v[62:65], off
	v_cvt_pk_bf16_f32 v54, v60, v61
	v_cvt_pk_bf16_f32 v55, v50, v51
	v_cvt_pk_bf16_f32 v56, v56, v57
	v_cvt_pk_bf16_f32 v57, v52, v53
	global_store_dwordx4 v[48:49], v[54:57], off offset:64
	v_pk_mul_f32 v[38:39], v[38:39], v[152:153] op_sel_hi:[1,0]
	v_pk_mul_f32 v[52:53], v[36:37], v[152:153] op_sel_hi:[1,0]
	v_pk_mul_f32 v[50:51], v[34:35], v[152:153] op_sel_hi:[1,0]
	v_pk_mul_f32 v[54:55], v[32:33], v[152:153] op_sel_hi:[1,0]
	v_pk_mul_f32 v[34:35], v[46:47], v[152:153] op_sel_hi:[1,0]
	v_pk_mul_f32 v[44:45], v[44:45], v[152:153] op_sel_hi:[1,0]
	v_pk_mul_f32 v[36:37], v[42:43], v[152:153] op_sel_hi:[1,0]
	s_and_b64 vcc, exec, s[38:39]
	v_pk_mul_f32 v[40:41], v[40:41], v[152:153] op_sel_hi:[1,0]
	s_cbranch_vccnz .LBB0_573
	v_pk_mul_f32 v[32:33], v[34:35], v[34:35]
	v_pk_fma_f32 v[32:33], v[36:37], v[36:37], v[32:33]
	v_pk_fma_f32 v[32:33], v[38:39], v[38:39], v[32:33]
	v_pk_fma_f32 v[32:33], v[40:41], v[40:41], v[32:33]
	v_pk_fma_f32 v[32:33], v[44:45], v[44:45], v[32:33]
	v_pk_fma_f32 v[32:33], v[50:51], v[50:51], v[32:33]
	v_pk_fma_f32 v[32:33], v[52:53], v[52:53], v[32:33]
	v_pk_fma_f32 v[32:33], v[54:55], v[54:55], v[32:33]
	v_add_f32_e32 v32, v32, v33
	v_mov_b32_e32 v33, v32
	s_nop 1
	v_permlane16_swap_b32_e32 v32, v33
	v_add_f32_e32 v32, v32, v33
	v_mov_b32_e32 v33, v32
	s_nop 1
	v_permlane32_swap_b32_e32 v32, v33
	v_add_f32_e32 v32, v32, v33
	v_fmamk_f32 v32, v32, 0x3c800000, v201
	v_rsq_f32_e32 v32, v32
	s_waitcnt lgkmcnt(0)
	v_pk_mul_f32 v[42:43], v[124:125], v[52:53]
	v_pk_mul_f32 v[38:39], v[126:127], v[38:39]
	v_pk_mul_f32 v[46:47], v[120:121], v[54:55]
	v_pk_mul_f32 v[52:53], v[42:43], v[32:33] op_sel_hi:[1,0]
	v_pk_mul_f32 v[42:43], v[122:123], v[50:51]
	v_pk_mul_f32 v[34:35], v[118:119], v[34:35]
	v_pk_mul_f32 v[50:51], v[42:43], v[32:33] op_sel_hi:[1,0]
	v_pk_mul_f32 v[42:43], v[116:117], v[44:45]
	v_pk_mul_f32 v[36:37], v[114:115], v[36:37]
	v_pk_mul_f32 v[40:41], v[112:113], v[40:41]
	v_pk_mul_f32 v[38:39], v[38:39], v[32:33] op_sel_hi:[1,0]
	v_pk_mul_f32 v[54:55], v[46:47], v[32:33] op_sel_hi:[1,0]
	v_pk_mul_f32 v[34:35], v[34:35], v[32:33] op_sel_hi:[1,0]
	v_pk_mul_f32 v[44:45], v[42:43], v[32:33] op_sel_hi:[1,0]
	v_pk_mul_f32 v[36:37], v[36:37], v[32:33] op_sel_hi:[1,0]
	v_pk_mul_f32 v[40:41], v[40:41], v[32:33] op_sel_hi:[1,0]
; __device__ __forceinline__ float sum_x16(float v) { float a, b; swap16(v, a, b); return a + b; }
; __device__ __forceinline__ float sum_x32(float v) { float a, b; swap32(v, a, b); return a + b; }
; __device__ __forceinline__ void st16_wt(void* p, u32x4 v) { if (WT_STORES) asm volatile("global_store_dwordx4 %0, %1, off sc1\n\ts_nop 1" :: "v"(p), "v"(v) : "memory"); else *(u32x4*)p = v; }
; __device__ __forceinline__ unsigned cvt_pk_bf16(float lo, float hi) { unsigned r; asm volatile("v_cvt_pk_bf16_f32 %0, %1, %2" : "=v"(r) : "v"(lo), "v"(hi)); return r; }
;     __device__ __forceinline__ void operator()(const f32x4 (&acc)[2][2][4][2], const Unit& u, int wr, int wc, int fr, int fq, const bool reuse, PG8_LAS float* rscr, PG8_LAS const float* gains) const {
;     ...
;                 if (type < 2) {
;                     float ss = 0.f;
; #pragma unroll
;                     for (int bj = 0; bj < 2; ++bj)
; #pragma unroll
;                         for (int n = 0; n < 2; ++n) { const f32x4 x = v[bj][n]; ss += (x[0] * x[0] + x[1] * x[1]) + (x[2] * x[2] + x[3] * x[3]); }
;                     ss = sum_x16(ss); ss = sum_x32(ss);
;                     const float inv = __builtin_amdgcn_rsqf(ss * (1.0f / 64.0f) + RMS_EPS);
; #pragma unroll
;                     for (int bj = 0; bj < 2; ++bj)
; #pragma unroll
;                         for (int n = 0; n < 2; ++n) v[bj][n] = v[bj][n] * gv[bj][n] * inv;
;                 }
;                 bf16_t* p = p0 + (size_t)(8 * ai + m) * step16;
; #pragma unroll
;                 for (int bj = 0; bj < 2; ++bj) { u32x4 w; w.x = cvt_pk_bf16(v[bj][0][0], v[bj][0][1]); w.y = cvt_pk_bf16(v[bj][0][2], v[bj][0][3]); w.z = cvt_pk_bf16(v[bj][1][0], v[bj][1][1]); w.w = cvt_pk_bf16(v[bj][1][2], v[bj][1][3]);
;                     st16_wt(p + 32 * bj, w); }
.LBB0_573:
	v_lshl_add_u64 v[32:33], v[48:49], 0, s[12:13]
	v_mov_b32_e32 v254, v32
	v_mov_b32_e32 v255, v33
	s_mov_b32 s100, s12
	v_cvt_pk_bf16_f32 v46, v52, v53
	v_cvt_pk_bf16_f32 v47, v38, v39
	v_cvt_pk_bf16_f32 v48, v54, v55
	v_cvt_pk_bf16_f32 v49, v50, v51
	v_mov_b32_e32 v228, v46
	v_mov_b32_e32 v229, v47
	v_mov_b32_e32 v230, v48
	v_mov_b32_e32 v231, v49
	v_cvt_pk_bf16_f32 v38, v44, v45
	v_cvt_pk_bf16_f32 v39, v34, v35
	v_cvt_pk_bf16_f32 v40, v40, v41
	v_cvt_pk_bf16_f32 v41, v36, v37
	v_mov_b32_e32 v232, v38
	v_mov_b32_e32 v233, v39
	v_mov_b32_e32 v234, v40
	v_mov_b32_e32 v235, v41
	v_pk_mul_f32 v[22:23], v[22:23], v[148:149] op_sel_hi:[1,0]
	v_pk_mul_f32 v[36:37], v[20:21], v[148:149] op_sel_hi:[1,0]
	v_pk_mul_f32 v[34:35], v[18:19], v[148:149] op_sel_hi:[1,0]
	v_pk_mul_f32 v[38:39], v[16:17], v[148:149] op_sel_hi:[1,0]
	v_pk_mul_f32 v[18:19], v[30:31], v[148:149] op_sel_hi:[1,0]
	v_pk_mul_f32 v[28:29], v[28:29], v[148:149] op_sel_hi:[1,0]
	v_pk_mul_f32 v[20:21], v[26:27], v[148:149] op_sel_hi:[1,0]
	s_and_b64 vcc, exec, s[38:39]
	v_pk_mul_f32 v[24:25], v[24:25], v[148:149] op_sel_hi:[1,0]
	s_cbranch_vccnz .LBB0_575
	v_pk_mul_f32 v[16:17], v[18:19], v[18:19]
	v_pk_fma_f32 v[16:17], v[20:21], v[20:21], v[16:17]
	v_pk_fma_f32 v[16:17], v[22:23], v[22:23], v[16:17]
	v_pk_fma_f32 v[16:17], v[24:25], v[24:25], v[16:17]
	v_pk_fma_f32 v[16:17], v[28:29], v[28:29], v[16:17]
	v_pk_fma_f32 v[16:17], v[34:35], v[34:35], v[16:17]
	v_pk_fma_f32 v[16:17], v[36:37], v[36:37], v[16:17]
	v_pk_fma_f32 v[16:17], v[38:39], v[38:39], v[16:17]
	v_add_f32_e32 v16, v16, v17
	v_mov_b32_e32 v17, v16
	s_nop 1
	v_permlane16_swap_b32_e32 v16, v17
	v_add_f32_e32 v16, v16, v17
	v_mov_b32_e32 v17, v16
	s_nop 1
	v_permlane32_swap_b32_e32 v16, v17
	v_add_f32_e32 v16, v16, v17
	v_fmamk_f32 v16, v16, 0x3c800000, v201
	v_rsq_f32_e32 v16, v16
	s_waitcnt lgkmcnt(0)
	v_pk_mul_f32 v[26:27], v[124:125], v[36:37]
	v_pk_mul_f32 v[22:23], v[126:127], v[22:23]
	v_pk_mul_f32 v[30:31], v[120:121], v[38:39]
	v_pk_mul_f32 v[36:37], v[26:27], v[16:17] op_sel_hi:[1,0]
	v_pk_mul_f32 v[26:27], v[122:123], v[34:35]
	v_pk_mul_f32 v[18:19], v[118:119], v[18:19]
	v_pk_mul_f32 v[34:35], v[26:27], v[16:17] op_sel_hi:[1,0]
	v_pk_mul_f32 v[26:27], v[116:117], v[28:29]
	v_pk_mul_f32 v[20:21], v[114:115], v[20:21]
	v_pk_mul_f32 v[24:25], v[112:113], v[24:25]
	v_pk_mul_f32 v[22:23], v[22:23], v[16:17] op_sel_hi:[1,0]
	v_pk_mul_f32 v[38:39], v[30:31], v[16:17] op_sel_hi:[1,0]
	v_pk_mul_f32 v[18:19], v[18:19], v[16:17] op_sel_hi:[1,0]
	v_pk_mul_f32 v[28:29], v[26:27], v[16:17] op_sel_hi:[1,0]
	v_pk_mul_f32 v[20:21], v[20:21], v[16:17] op_sel_hi:[1,0]
	v_pk_mul_f32 v[24:25], v[24:25], v[16:17] op_sel_hi:[1,0]
.LBB0_575:
	v_lshl_add_u64 v[16:17], v[32:33], 0, s[12:13]
	v_cvt_pk_bf16_f32 v30, v36, v37
	v_cvt_pk_bf16_f32 v31, v22, v23
	v_cvt_pk_bf16_f32 v32, v38, v39
	v_cvt_pk_bf16_f32 v33, v34, v35
	v_mov_b32_e32 v236, v30
	v_mov_b32_e32 v237, v31
	v_mov_b32_e32 v238, v32
	v_mov_b32_e32 v239, v33
	v_cvt_pk_bf16_f32 v22, v28, v29
	v_cvt_pk_bf16_f32 v23, v18, v19
	v_cvt_pk_bf16_f32 v24, v24, v25
	v_cvt_pk_bf16_f32 v25, v20, v21
	v_pk_mul_f32 v[6:7], v[6:7], v[144:145] op_sel_hi:[1,0]
	v_pk_mul_f32 v[18:19], v[4:5], v[144:145] op_sel_hi:[1,0]
	v_pk_mul_f32 v[4:5], v[2:3], v[144:145] op_sel_hi:[1,0]
	v_pk_mul_f32 v[20:21], v[0:1], v[144:145] op_sel_hi:[1,0]
	v_pk_mul_f32 v[0:1], v[14:15], v[144:145] op_sel_hi:[1,0]
	v_pk_mul_f32 v[12:13], v[12:13], v[144:145] op_sel_hi:[1,0]
	v_pk_mul_f32 v[2:3], v[10:11], v[144:145] op_sel_hi:[1,0]
	s_and_b64 vcc, exec, s[38:39]
	v_pk_mul_f32 v[8:9], v[8:9], v[144:145] op_sel_hi:[1,0]
	v_mov_b32_e32 v240, v22
	v_mov_b32_e32 v241, v23
	v_mov_b32_e32 v242, v24
	v_mov_b32_e32 v243, v25
	s_cbranch_vccnz .LBB0_577
	v_pk_mul_f32 v[10:11], v[0:1], v[0:1]
	v_pk_fma_f32 v[10:11], v[2:3], v[2:3], v[10:11]
	v_pk_fma_f32 v[10:11], v[4:5], v[4:5], v[10:11]
	v_pk_fma_f32 v[10:11], v[6:7], v[6:7], v[10:11]
	v_pk_fma_f32 v[10:11], v[8:9], v[8:9], v[10:11]
	v_pk_fma_f32 v[10:11], v[12:13], v[12:13], v[10:11]
	v_pk_fma_f32 v[10:11], v[18:19], v[18:19], v[10:11]
	v_pk_fma_f32 v[10:11], v[20:21], v[20:21], v[10:11]
	v_add_f32_e32 v10, v10, v11
	v_mov_b32_e32 v11, v10
	s_nop 1
	v_permlane16_swap_b32_e32 v10, v11
	v_add_f32_e32 v10, v10, v11
	v_mov_b32_e32 v11, v10
	s_nop 1
	v_permlane32_swap_b32_e32 v10, v11
	v_add_f32_e32 v10, v10, v11
	v_fmamk_f32 v10, v10, 0x3c800000, v201
	v_rsq_f32_e32 v10, v10
	s_waitcnt lgkmcnt(0)
	v_pk_mul_f32 v[14:15], v[124:125], v[18:19]
	v_pk_mul_f32 v[6:7], v[126:127], v[6:7]
	v_pk_mul_f32 v[4:5], v[122:123], v[4:5]
	v_pk_mul_f32 v[18:19], v[14:15], v[10:11] op_sel_hi:[1,0]
	v_pk_mul_f32 v[14:15], v[120:121], v[20:21]
	v_pk_mul_f32 v[0:1], v[118:119], v[0:1]
	v_pk_mul_f32 v[12:13], v[116:117], v[12:13]
	v_pk_mul_f32 v[2:3], v[114:115], v[2:3]
	v_pk_mul_f32 v[8:9], v[112:113], v[8:9]
	v_pk_mul_f32 v[6:7], v[6:7], v[10:11] op_sel_hi:[1,0]
	v_pk_mul_f32 v[4:5], v[4:5], v[10:11] op_sel_hi:[1,0]
	v_pk_mul_f32 v[20:21], v[14:15], v[10:11] op_sel_hi:[1,0]
	v_pk_mul_f32 v[0:1], v[0:1], v[10:11] op_sel_hi:[1,0]
	v_pk_mul_f32 v[12:13], v[12:13], v[10:11] op_sel_hi:[1,0]
	v_pk_mul_f32 v[2:3], v[2:3], v[10:11] op_sel_hi:[1,0]
	v_pk_mul_f32 v[8:9], v[8:9], v[10:11] op_sel_hi:[1,0]
